# accumulator zeroing with 64 v_mov_b64 per unit instead of 128 v_mov_b32 in all 6 GEMM phases
# speedup vs baseline: 1.0061x; 1.0023x over previous
; template <class Epi, class Sched, bool ALIGN_EPI = false, bool SP2 = false>
; __device__ __forceinline__ void gemm_phase(PG8_LAS unsigned char* lds, const Gemm g, const Sched& S, const Epi& E) {
;     ...
;         const bool has_next = S.next(ui + 1, nxt);
;         const char* nA = has_next ? (const char*)g.A + (size_t)nxt.pm * tstep : cA; const char* nB = has_next ? (const char*)g.Bt + (size_t)nxt.pn * tstep : cB;
;     ...
; #pragma unroll
;         for (int a = 0; a < 2; ++a)
; #pragma unroll
;             for (int b = 0; b < 2; ++b)
; #pragma unroll
;                 for (int m = 0; m < 4; ++m)
; #pragma unroll
;                     for (int n = 0; n < 2; ++n) acc[a][b][m][n] = (f32x4){0.f, 0.f, 0.f, 0.f};
.LBB0_133:
	s_ashr_i32 s27, s26, 31
	s_lshl_b64 s[28:29], s[26:27], 19
	s_add_u32 s28, s76, s28
	s_addc_u32 s29, s77, s29
	s_and_b64 s[30:31], s[4:5], exec
	s_cselect_b32 s1, s29, s35
	s_cselect_b32 s7, s28, s34
	s_ashr_i32 s15, s14, 31
	s_lshl_b64 s[30:31], s[14:15], 19
	s_add_u32 s30, s24, s30
	s_addc_u32 s31, s25, s31
	s_and_b64 s[38:39], s[4:5], exec
	s_cselect_b32 s15, s31, s37
	s_cselect_b32 s27, s30, s36
	s_add_u32 s34, s34, 0x40080
	s_addc_u32 s35, s35, 0
	s_add_u32 s87, s36, 0x100
	v_mov_b64_e32 v[0:1], 0
	v_mov_b64_e32 v[2:3], 0
	v_mov_b64_e32 v[4:5], 0
	v_mov_b64_e32 v[6:7], 0
	v_mov_b64_e32 v[8:9], 0
	v_mov_b64_e32 v[10:11], 0
	v_mov_b64_e32 v[12:13], 0
	v_mov_b64_e32 v[14:15], 0
	v_mov_b64_e32 v[16:17], 0
	v_mov_b64_e32 v[18:19], 0
	v_mov_b64_e32 v[20:21], 0
	v_mov_b64_e32 v[22:23], 0
	v_mov_b64_e32 v[24:25], 0
	v_mov_b64_e32 v[26:27], 0
	v_mov_b64_e32 v[28:29], 0
	v_mov_b64_e32 v[30:31], 0
	v_mov_b64_e32 v[32:33], 0
	v_mov_b64_e32 v[34:35], 0
	v_mov_b64_e32 v[36:37], 0
	v_mov_b64_e32 v[38:39], 0
	v_mov_b64_e32 v[40:41], 0
	v_mov_b64_e32 v[42:43], 0
	v_mov_b64_e32 v[44:45], 0
	v_mov_b64_e32 v[46:47], 0
	v_mov_b64_e32 v[48:49], 0
	v_mov_b64_e32 v[50:51], 0
	v_mov_b64_e32 v[52:53], 0
	v_mov_b64_e32 v[54:55], 0
	v_mov_b64_e32 v[56:57], 0
	v_mov_b64_e32 v[58:59], 0
	v_mov_b64_e32 v[60:61], 0
	v_mov_b64_e32 v[62:63], 0
	v_mov_b64_e32 v[64:65], 0
	v_mov_b64_e32 v[66:67], 0
	v_mov_b64_e32 v[68:69], 0
	v_mov_b64_e32 v[70:71], 0
	v_mov_b64_e32 v[72:73], 0
	v_mov_b64_e32 v[74:75], 0
	v_mov_b64_e32 v[76:77], 0
	v_mov_b64_e32 v[78:79], 0
	v_mov_b64_e32 v[80:81], 0
	v_mov_b64_e32 v[82:83], 0
	v_mov_b64_e32 v[84:85], 0
	v_mov_b64_e32 v[86:87], 0
	v_mov_b64_e32 v[88:89], 0
	v_mov_b64_e32 v[90:91], 0
	v_mov_b64_e32 v[92:93], 0
	v_mov_b64_e32 v[94:95], 0
	v_mov_b64_e32 v[96:97], 0
	v_mov_b64_e32 v[98:99], 0
	v_mov_b64_e32 v[100:101], 0
	v_mov_b64_e32 v[102:103], 0
	v_mov_b64_e32 v[104:105], 0
	v_mov_b64_e32 v[106:107], 0
	v_mov_b64_e32 v[108:109], 0
	v_mov_b64_e32 v[110:111], 0
	v_mov_b64_e32 v[112:113], 0
	v_mov_b64_e32 v[114:115], 0
	v_mov_b64_e32 v[116:117], 0
	v_mov_b64_e32 v[118:119], 0
	v_mov_b64_e32 v[120:121], 0
	v_mov_b64_e32 v[122:123], 0
	v_mov_b64_e32 v[124:125], 0
	v_mov_b64_e32 v[126:127], 0
	s_addc_u32 s88, s37, 0
	s_mov_b32 s89, -2

; template <class Epi, class Sched, bool ALIGN_EPI = false, bool SP2 = false>
; __device__ __forceinline__ void gemm_phase(PG8_LAS unsigned char* lds, const Gemm g, const Sched& S, const Epi& E) {
;     ...
;         const bool has_next = S.next(ui + 1, nxt);
;         const char* nA = has_next ? (const char*)g.A + (size_t)nxt.pm * tstep : cA; const char* nB = has_next ? (const char*)g.Bt + (size_t)nxt.pn * tstep : cB;
;     ...
; #pragma unroll
;         for (int a = 0; a < 2; ++a)
; #pragma unroll
;             for (int b = 0; b < 2; ++b)
; #pragma unroll
;                 for (int m = 0; m < 4; ++m)
; #pragma unroll
;                     for (int n = 0; n < 2; ++n) acc[a][b][m][n] = (f32x4){0.f, 0.f, 0.f, 0.f};
.LBB0_371:
	s_add_u32 s20, s20, 0xb0080
	s_addc_u32 s21, s21, 0
	s_add_u32 s46, s24, 0x100
	v_mov_b64_e32 v[0:1], 0
	v_mov_b64_e32 v[2:3], 0
	v_mov_b64_e32 v[4:5], 0
	v_mov_b64_e32 v[6:7], 0
	v_mov_b64_e32 v[8:9], 0
	v_mov_b64_e32 v[10:11], 0
	v_mov_b64_e32 v[12:13], 0
	v_mov_b64_e32 v[14:15], 0
	v_mov_b64_e32 v[16:17], 0
	v_mov_b64_e32 v[18:19], 0
	v_mov_b64_e32 v[20:21], 0
	v_mov_b64_e32 v[22:23], 0
	v_mov_b64_e32 v[24:25], 0
	v_mov_b64_e32 v[26:27], 0
	v_mov_b64_e32 v[28:29], 0
	v_mov_b64_e32 v[30:31], 0
	v_mov_b64_e32 v[32:33], 0
	v_mov_b64_e32 v[34:35], 0
	v_mov_b64_e32 v[36:37], 0
	v_mov_b64_e32 v[38:39], 0
	v_mov_b64_e32 v[40:41], 0
	v_mov_b64_e32 v[42:43], 0
	v_mov_b64_e32 v[44:45], 0
	v_mov_b64_e32 v[46:47], 0
	v_mov_b64_e32 v[48:49], 0
	v_mov_b64_e32 v[50:51], 0
	v_mov_b64_e32 v[52:53], 0
	v_mov_b64_e32 v[54:55], 0
	v_mov_b64_e32 v[56:57], 0
	v_mov_b64_e32 v[58:59], 0
	v_mov_b64_e32 v[60:61], 0
	v_mov_b64_e32 v[62:63], 0
	v_mov_b64_e32 v[64:65], 0
	v_mov_b64_e32 v[66:67], 0
	v_mov_b64_e32 v[68:69], 0
	v_mov_b64_e32 v[70:71], 0
	v_mov_b64_e32 v[72:73], 0
	v_mov_b64_e32 v[74:75], 0
	v_mov_b64_e32 v[76:77], 0
	v_mov_b64_e32 v[78:79], 0
	v_mov_b64_e32 v[80:81], 0
	v_mov_b64_e32 v[82:83], 0
	v_mov_b64_e32 v[84:85], 0
	v_mov_b64_e32 v[86:87], 0
	v_mov_b64_e32 v[88:89], 0
	v_mov_b64_e32 v[90:91], 0
	v_mov_b64_e32 v[92:93], 0
	v_mov_b64_e32 v[94:95], 0
	v_mov_b64_e32 v[96:97], 0
	v_mov_b64_e32 v[98:99], 0
	v_mov_b64_e32 v[100:101], 0
	v_mov_b64_e32 v[102:103], 0
	v_mov_b64_e32 v[104:105], 0
	v_mov_b64_e32 v[106:107], 0
	v_mov_b64_e32 v[108:109], 0
	v_mov_b64_e32 v[110:111], 0
	v_mov_b64_e32 v[112:113], 0
	v_mov_b64_e32 v[114:115], 0
	v_mov_b64_e32 v[116:117], 0
	v_mov_b64_e32 v[118:119], 0
	v_mov_b64_e32 v[120:121], 0
	v_mov_b64_e32 v[122:123], 0
	v_mov_b64_e32 v[124:125], 0
	v_mov_b64_e32 v[126:127], 0
	s_addc_u32 s47, s25, 0
	s_mov_b32 s54, -2
	s_waitcnt lgkmcnt(0)

; template <class Epi, class Sched, bool ALIGN_EPI = false, bool SP2 = false>
; __device__ __forceinline__ void gemm_phase(PG8_LAS unsigned char* lds, const Gemm g, const Sched& S, const Epi& E) {
;     ...
;         const bool has_next = S.next(ui + 1, nxt);
;         const char* nA = has_next ? (const char*)g.A + (size_t)nxt.pm * tstep : cA; const char* nB = has_next ? (const char*)g.Bt + (size_t)nxt.pn * tstep : cB;
;     ...
; #pragma unroll
;         for (int a = 0; a < 2; ++a)
; #pragma unroll
;             for (int b = 0; b < 2; ++b)
; #pragma unroll
;                 for (int m = 0; m < 4; ++m)
; #pragma unroll
;                     for (int n = 0; n < 2; ++n) acc[a][b][m][n] = (f32x4){0.f, 0.f, 0.f, 0.f};
.LBB0_463:
	s_ashr_i32 s21, s20, 31
	s_lshl_b64 s[24:25], s[20:21], 19
	s_add_u32 s24, s76, s24
	s_addc_u32 s25, s77, s25
	s_and_b64 s[26:27], s[10:11], exec
	s_cselect_b32 s13, s25, s1
	s_cselect_b32 s21, s24, s0
	s_ashr_i32 s19, s18, 31
	s_lshl_b64 s[26:27], s[18:19], 19
	s_add_u32 s26, s33, s26
	s_addc_u32 s27, s36, s27
	s_and_b64 s[34:35], s[10:11], exec
	s_cselect_b32 s19, s27, s31
	s_cselect_b32 s58, s26, s30
	s_add_u32 s0, s0, 0x40080
	s_addc_u32 s1, s1, 0
	s_add_u32 s59, s30, 0x100
	v_mov_b64_e32 v[0:1], 0
	v_mov_b64_e32 v[2:3], 0
	v_mov_b64_e32 v[4:5], 0
	v_mov_b64_e32 v[6:7], 0
	v_mov_b64_e32 v[8:9], 0
	v_mov_b64_e32 v[10:11], 0
	v_mov_b64_e32 v[12:13], 0
	v_mov_b64_e32 v[14:15], 0
	v_mov_b64_e32 v[16:17], 0
	v_mov_b64_e32 v[18:19], 0
	v_mov_b64_e32 v[20:21], 0
	v_mov_b64_e32 v[22:23], 0
	v_mov_b64_e32 v[24:25], 0
	v_mov_b64_e32 v[26:27], 0
	v_mov_b64_e32 v[28:29], 0
	v_mov_b64_e32 v[30:31], 0
	v_mov_b64_e32 v[32:33], 0
	v_mov_b64_e32 v[34:35], 0
	v_mov_b64_e32 v[36:37], 0
	v_mov_b64_e32 v[38:39], 0
	v_mov_b64_e32 v[40:41], 0
	v_mov_b64_e32 v[42:43], 0
	v_mov_b64_e32 v[44:45], 0
	v_mov_b64_e32 v[46:47], 0
	v_mov_b64_e32 v[48:49], 0
	v_mov_b64_e32 v[50:51], 0
	v_mov_b64_e32 v[52:53], 0
	v_mov_b64_e32 v[54:55], 0
	v_mov_b64_e32 v[56:57], 0
	v_mov_b64_e32 v[58:59], 0
	v_mov_b64_e32 v[60:61], 0
	v_mov_b64_e32 v[62:63], 0
	v_mov_b64_e32 v[64:65], 0
	v_mov_b64_e32 v[66:67], 0
	v_mov_b64_e32 v[68:69], 0
	v_mov_b64_e32 v[70:71], 0
	v_mov_b64_e32 v[72:73], 0
	v_mov_b64_e32 v[74:75], 0
	v_mov_b64_e32 v[76:77], 0
	v_mov_b64_e32 v[78:79], 0
	v_mov_b64_e32 v[80:81], 0
	v_mov_b64_e32 v[82:83], 0
	v_mov_b64_e32 v[84:85], 0
	v_mov_b64_e32 v[86:87], 0
	v_mov_b64_e32 v[88:89], 0
	v_mov_b64_e32 v[90:91], 0
	v_mov_b64_e32 v[92:93], 0
	v_mov_b64_e32 v[94:95], 0
	v_mov_b64_e32 v[96:97], 0
	v_mov_b64_e32 v[98:99], 0
	v_mov_b64_e32 v[100:101], 0
	v_mov_b64_e32 v[102:103], 0
	v_mov_b64_e32 v[104:105], 0
	v_mov_b64_e32 v[106:107], 0
	v_mov_b64_e32 v[108:109], 0
	v_mov_b64_e32 v[110:111], 0
	v_mov_b64_e32 v[112:113], 0
	v_mov_b64_e32 v[114:115], 0
	v_mov_b64_e32 v[116:117], 0
	v_mov_b64_e32 v[118:119], 0
	v_mov_b64_e32 v[120:121], 0
	v_mov_b64_e32 v[122:123], 0
	v_mov_b64_e32 v[124:125], 0
	v_mov_b64_e32 v[126:127], 0
	s_addc_u32 s80, s31, 0
	s_mov_b32 s81, -2

; template <class Epi, class Sched, bool ALIGN_EPI = false, bool SP2 = false>
; __device__ __forceinline__ void gemm_phase(PG8_LAS unsigned char* lds, const Gemm g, const Sched& S, const Epi& E) {
;     ...
;         const bool has_next = S.next(ui + 1, nxt);
;         const char* nA = has_next ? (const char*)g.A + (size_t)nxt.pm * tstep : cA; const char* nB = has_next ? (const char*)g.Bt + (size_t)nxt.pn * tstep : cB;
;     ...
; #pragma unroll
;         for (int a = 0; a < 2; ++a)
; #pragma unroll
;             for (int b = 0; b < 2; ++b)
; #pragma unroll
;                 for (int m = 0; m < 4; ++m)
; #pragma unroll
;                     for (int n = 0; n < 2; ++n) acc[a][b][m][n] = (f32x4){0.f, 0.f, 0.f, 0.f};
.LBB0_1229:
	s_ashr_i32 s19, s18, 31
	s_lshl_b64 s[20:21], s[18:19], 19
	s_add_u32 s20, s48, s20
	s_addc_u32 s21, s49, s21
	s_and_b64 s[22:23], s[10:11], exec
	s_cselect_b32 s19, s21, s27
	s_cselect_b32 s25, s20, s26
	s_ashr_i32 s17, s16, 31
	s_lshl_b64 s[22:23], s[16:17], 19
	s_add_u32 s22, s2, s22
	s_addc_u32 s23, s3, s23
	s_and_b64 s[30:31], s[10:11], exec
	s_cselect_b32 s17, s23, s29
	s_cselect_b32 s47, s22, s28
	s_add_u32 s26, s26, 0x40080
	s_addc_u32 s27, s27, 0
	s_add_u32 s50, s28, 0x100
	v_mov_b64_e32 v[0:1], 0
	v_mov_b64_e32 v[2:3], 0
	v_mov_b64_e32 v[4:5], 0
	v_mov_b64_e32 v[6:7], 0
	v_mov_b64_e32 v[8:9], 0
	v_mov_b64_e32 v[10:11], 0
	v_mov_b64_e32 v[12:13], 0
	v_mov_b64_e32 v[14:15], 0
	v_mov_b64_e32 v[16:17], 0
	v_mov_b64_e32 v[18:19], 0
	v_mov_b64_e32 v[20:21], 0
	v_mov_b64_e32 v[22:23], 0
	v_mov_b64_e32 v[24:25], 0
	v_mov_b64_e32 v[26:27], 0
	v_mov_b64_e32 v[28:29], 0
	v_mov_b64_e32 v[30:31], 0
	v_mov_b64_e32 v[32:33], 0
	v_mov_b64_e32 v[34:35], 0
	v_mov_b64_e32 v[36:37], 0
	v_mov_b64_e32 v[38:39], 0
	v_mov_b64_e32 v[40:41], 0
	v_mov_b64_e32 v[42:43], 0
	v_mov_b64_e32 v[44:45], 0
	v_mov_b64_e32 v[46:47], 0
	v_mov_b64_e32 v[48:49], 0
	v_mov_b64_e32 v[50:51], 0
	v_mov_b64_e32 v[52:53], 0
	v_mov_b64_e32 v[54:55], 0
	v_mov_b64_e32 v[56:57], 0
	v_mov_b64_e32 v[58:59], 0
	v_mov_b64_e32 v[60:61], 0
	v_mov_b64_e32 v[62:63], 0
	v_mov_b64_e32 v[64:65], 0
	v_mov_b64_e32 v[66:67], 0
	v_mov_b64_e32 v[68:69], 0
	v_mov_b64_e32 v[70:71], 0
	v_mov_b64_e32 v[72:73], 0
	v_mov_b64_e32 v[74:75], 0
	v_mov_b64_e32 v[76:77], 0
	v_mov_b64_e32 v[78:79], 0
	v_mov_b64_e32 v[80:81], 0
	v_mov_b64_e32 v[82:83], 0
	v_mov_b64_e32 v[84:85], 0
	v_mov_b64_e32 v[86:87], 0
	v_mov_b64_e32 v[88:89], 0
	v_mov_b64_e32 v[90:91], 0
	v_mov_b64_e32 v[92:93], 0
	v_mov_b64_e32 v[94:95], 0
	v_mov_b64_e32 v[96:97], 0
	v_mov_b64_e32 v[98:99], 0
	v_mov_b64_e32 v[100:101], 0
	v_mov_b64_e32 v[102:103], 0
	v_mov_b64_e32 v[104:105], 0
	v_mov_b64_e32 v[106:107], 0
	v_mov_b64_e32 v[108:109], 0
	v_mov_b64_e32 v[110:111], 0
	v_mov_b64_e32 v[112:113], 0
	v_mov_b64_e32 v[114:115], 0
	v_mov_b64_e32 v[116:117], 0
	v_mov_b64_e32 v[118:119], 0
	v_mov_b64_e32 v[120:121], 0
	v_mov_b64_e32 v[122:123], 0
	v_mov_b64_e32 v[124:125], 0
	v_mov_b64_e32 v[126:127], 0
	s_addc_u32 s51, s29, 0
	s_mov_b32 s52, -2
	s_waitcnt lgkmcnt(0)

; template <class Epi, class Sched, bool ALIGN_EPI = false, bool SP2 = false>
; __device__ __forceinline__ void gemm_phase(PG8_LAS unsigned char* lds, const Gemm g, const Sched& S, const Epi& E) {
;     ...
;         const bool has_next = S.next(ui + 1, nxt);
;         const char* nA = has_next ? (const char*)g.A + (size_t)nxt.pm * tstep : cA; const char* nB = has_next ? (const char*)g.Bt + (size_t)nxt.pn * tstep : cB;
;     ...
; #pragma unroll
;         for (int a = 0; a < 2; ++a)
; #pragma unroll
;             for (int b = 0; b < 2; ++b)
; #pragma unroll
;                 for (int m = 0; m < 4; ++m)
; #pragma unroll
;                     for (int n = 0; n < 2; ++n) acc[a][b][m][n] = (f32x4){0.f, 0.f, 0.f, 0.f};
.LBB0_1321:
	s_ashr_i32 s19, s18, 31
	s_lshl_b64 s[20:21], s[18:19], 19
	s_add_u32 s20, s76, s20
	s_addc_u32 s21, s77, s21
	s_and_b64 s[22:23], s[8:9], exec
	s_cselect_b32 s1, s21, s25
	s_cselect_b32 s11, s20, s24
	s_ashr_i32 s17, s16, 31
	s_lshl_b64 s[22:23], s[16:17], 19
	s_add_u32 s22, s30, s22
	s_addc_u32 s23, s31, s23
	s_and_b64 s[28:29], s[8:9], exec
	s_cselect_b32 s17, s23, s27
	s_cselect_b32 s19, s22, s26
	s_add_u32 s24, s24, 0x40080
	s_addc_u32 s25, s25, 0
	s_add_u32 s48, s26, 0x100
	v_mov_b64_e32 v[0:1], 0
	v_mov_b64_e32 v[2:3], 0
	v_mov_b64_e32 v[4:5], 0
	v_mov_b64_e32 v[6:7], 0
	v_mov_b64_e32 v[8:9], 0
	v_mov_b64_e32 v[10:11], 0
	v_mov_b64_e32 v[12:13], 0
	v_mov_b64_e32 v[14:15], 0
	v_mov_b64_e32 v[16:17], 0
	v_mov_b64_e32 v[18:19], 0
	v_mov_b64_e32 v[20:21], 0
	v_mov_b64_e32 v[22:23], 0
	v_mov_b64_e32 v[24:25], 0
	v_mov_b64_e32 v[26:27], 0
	v_mov_b64_e32 v[28:29], 0
	v_mov_b64_e32 v[30:31], 0
	v_mov_b64_e32 v[32:33], 0
	v_mov_b64_e32 v[34:35], 0
	v_mov_b64_e32 v[36:37], 0
	v_mov_b64_e32 v[38:39], 0
	v_mov_b64_e32 v[40:41], 0
	v_mov_b64_e32 v[42:43], 0
	v_mov_b64_e32 v[44:45], 0
	v_mov_b64_e32 v[46:47], 0
	v_mov_b64_e32 v[48:49], 0
	v_mov_b64_e32 v[50:51], 0
	v_mov_b64_e32 v[52:53], 0
	v_mov_b64_e32 v[54:55], 0
	v_mov_b64_e32 v[56:57], 0
	v_mov_b64_e32 v[58:59], 0
	v_mov_b64_e32 v[60:61], 0
	v_mov_b64_e32 v[62:63], 0
	v_mov_b64_e32 v[64:65], 0
	v_mov_b64_e32 v[66:67], 0
	v_mov_b64_e32 v[68:69], 0
	v_mov_b64_e32 v[70:71], 0
	v_mov_b64_e32 v[72:73], 0
	v_mov_b64_e32 v[74:75], 0
	v_mov_b64_e32 v[76:77], 0
	v_mov_b64_e32 v[78:79], 0
	v_mov_b64_e32 v[80:81], 0
	v_mov_b64_e32 v[82:83], 0
	v_mov_b64_e32 v[84:85], 0
	v_mov_b64_e32 v[86:87], 0
	v_mov_b64_e32 v[88:89], 0
	v_mov_b64_e32 v[90:91], 0
	v_mov_b64_e32 v[92:93], 0
	v_mov_b64_e32 v[94:95], 0
	v_mov_b64_e32 v[96:97], 0
	v_mov_b64_e32 v[98:99], 0
	v_mov_b64_e32 v[100:101], 0
	v_mov_b64_e32 v[102:103], 0
	v_mov_b64_e32 v[104:105], 0
	v_mov_b64_e32 v[106:107], 0
	v_mov_b64_e32 v[108:109], 0
	v_mov_b64_e32 v[110:111], 0
	v_mov_b64_e32 v[112:113], 0
	v_mov_b64_e32 v[114:115], 0
	v_mov_b64_e32 v[116:117], 0
	v_mov_b64_e32 v[118:119], 0
	v_mov_b64_e32 v[120:121], 0
	v_mov_b64_e32 v[122:123], 0
	v_mov_b64_e32 v[124:125], 0
	v_mov_b64_e32 v[126:127], 0
	s_addc_u32 s49, s27, 0
	s_mov_b32 s50, -2

; template <class Epi, class Sched, bool ALIGN_EPI = false, bool SP2 = false>
; __device__ __forceinline__ void gemm_phase(PG8_LAS unsigned char* lds, const Gemm g, const Sched& S, const Epi& E) {
;     ...
;         const bool has_next = S.next(ui + 1, nxt);
;         const char* nA = has_next ? (const char*)g.A + (size_t)nxt.pm * tstep : cA; const char* nB = has_next ? (const char*)g.Bt + (size_t)nxt.pn * tstep : cB;
;     ...
; #pragma unroll
;         for (int a = 0; a < 2; ++a)
; #pragma unroll
;             for (int b = 0; b < 2; ++b)
; #pragma unroll
;                 for (int m = 0; m < 4; ++m)
; #pragma unroll
;                     for (int n = 0; n < 2; ++n) acc[a][b][m][n] = (f32x4){0.f, 0.f, 0.f, 0.f};
.LBB0_1441:
	s_add_u32 s6, s26, 0xb0080
	s_addc_u32 s7, s27, 0
	s_add_u32 s48, s10, 0x100
	v_mov_b64_e32 v[0:1], 0
	v_mov_b64_e32 v[2:3], 0
	v_mov_b64_e32 v[4:5], 0
	v_mov_b64_e32 v[6:7], 0
	v_mov_b64_e32 v[8:9], 0
	v_mov_b64_e32 v[10:11], 0
	v_mov_b64_e32 v[12:13], 0
	v_mov_b64_e32 v[14:15], 0
	v_mov_b64_e32 v[16:17], 0
	v_mov_b64_e32 v[18:19], 0
	v_mov_b64_e32 v[20:21], 0
	v_mov_b64_e32 v[22:23], 0
	v_mov_b64_e32 v[24:25], 0
	v_mov_b64_e32 v[26:27], 0
	v_mov_b64_e32 v[28:29], 0
	v_mov_b64_e32 v[30:31], 0
	v_mov_b64_e32 v[32:33], 0
	v_mov_b64_e32 v[34:35], 0
	v_mov_b64_e32 v[36:37], 0
	v_mov_b64_e32 v[38:39], 0
	v_mov_b64_e32 v[40:41], 0
	v_mov_b64_e32 v[42:43], 0
	v_mov_b64_e32 v[44:45], 0
	v_mov_b64_e32 v[46:47], 0
	v_mov_b64_e32 v[48:49], 0
	v_mov_b64_e32 v[50:51], 0
	v_mov_b64_e32 v[52:53], 0
	v_mov_b64_e32 v[54:55], 0
	v_mov_b64_e32 v[56:57], 0
	v_mov_b64_e32 v[58:59], 0
	v_mov_b64_e32 v[60:61], 0
	v_mov_b64_e32 v[62:63], 0
	v_mov_b64_e32 v[64:65], 0
	v_mov_b64_e32 v[66:67], 0
	v_mov_b64_e32 v[68:69], 0
	v_mov_b64_e32 v[70:71], 0
	v_mov_b64_e32 v[72:73], 0
	v_mov_b64_e32 v[74:75], 0
	v_mov_b64_e32 v[76:77], 0
	v_mov_b64_e32 v[78:79], 0
	v_mov_b64_e32 v[80:81], 0
	v_mov_b64_e32 v[82:83], 0
	v_mov_b64_e32 v[84:85], 0
	v_mov_b64_e32 v[86:87], 0
	v_mov_b64_e32 v[88:89], 0
	v_mov_b64_e32 v[90:91], 0
	v_mov_b64_e32 v[92:93], 0
	v_mov_b64_e32 v[94:95], 0
	v_mov_b64_e32 v[96:97], 0
	v_mov_b64_e32 v[98:99], 0
	v_mov_b64_e32 v[100:101], 0
	v_mov_b64_e32 v[102:103], 0
	v_mov_b64_e32 v[104:105], 0
	v_mov_b64_e32 v[106:107], 0
	v_mov_b64_e32 v[108:109], 0
	v_mov_b64_e32 v[110:111], 0
	v_mov_b64_e32 v[112:113], 0
	v_mov_b64_e32 v[114:115], 0
	v_mov_b64_e32 v[116:117], 0
	v_mov_b64_e32 v[118:119], 0
	v_mov_b64_e32 v[120:121], 0
	v_mov_b64_e32 v[122:123], 0
	v_mov_b64_e32 v[124:125], 0
	v_mov_b64_e32 v[126:127], 0
	s_addc_u32 s49, s11, 0
	s_mov_b32 s50, -2
